# grid barrier: non-leader workgroups poll the global generation word (one hop fewer in the release); + early acquire invalidate, conv de-serialised, swapped-V, nop drop, preamble burst
# speedup vs baseline: 1.0085x; 1.0085x over previous
; __device__ __forceinline__ unsigned xb_ld(unsigned* p)              { return __hip_atomic_load(p, __ATOMIC_RELAXED, __HIP_MEMORY_SCOPE_AGENT); }
; __device__ __forceinline__ unsigned xb_add(unsigned* p, unsigned v) { return __hip_atomic_fetch_add(p, v, __ATOMIC_RELAXED, __HIP_MEMORY_SCOPE_AGENT); }
; #define XB_SPIN(cond, bar) do { unsigned _sp = 0; while (cond) { __builtin_amdgcn_s_sleep(1); \
;     if ((++_sp & 255u) == 0u) { if (xb_ld(&(bar)[XB_TMO])) break; if (_sp > XB_SPIN_CAP) { atomicAdd(&(bar)[XB_TMO], 1u); break; } } } } while (0)
; __device__ __forceinline__ void xcd_barrier(const XcdBarrier& b) {
;     ...
;         const unsigned old = xb_add(&bar[XB_XSUB(b.x)], 1u);
;         const unsigned gen = old / nloc;
;         if (old + 1u == (gen + 1u) * nloc) {
;             __builtin_amdgcn_fence(__ATOMIC_RELEASE, "agent");
;             asm volatile("s_waitcnt vmcnt(0)" ::: "memory");
;             const unsigned og = xb_add(&bar[XB_TOP], 1u);
;             const unsigned tg = og / nx;
;             if (og + 1u == (tg + 1u) * nx) xb_add(&bar[XB_TOPGEN], 1u);
;             else XB_SPIN(xb_ld(&bar[XB_TOPGEN]) == tg, bar);
;             __builtin_amdgcn_fence(__ATOMIC_ACQUIRE, "agent");
;             xb_add(&bar[XB_XGEN(b.x)], 1u);
;             asm volatile("s_waitcnt vmcnt(0)" ::: "memory");
;         } else {
;             XB_SPIN(xb_ld(&bar[XB_XGEN(b.x)]) == gen, bar);
;             __builtin_amdgcn_fence(__ATOMIC_ACQUIRE, "agent");
;             asm volatile("s_waitcnt vmcnt(0)" ::: "memory");
;         }
.LBB0_61:
	s_or_b64 exec, exec, s[12:13]
	v_cvt_f32_u32_e32 v4, v2
	s_waitcnt vmcnt(0)
	v_readfirstlane_b32 s0, v3
	buffer_inv sc1
	v_sub_u32_e32 v3, 0, v2
	v_rcp_iflag_f32_e32 v4, v4
	v_add_u32_e32 v5, s0, v1
	v_mul_f32_e32 v4, 0x4f7ffffe, v4
	v_cvt_u32_f32_e32 v4, v4
	v_mul_lo_u32 v1, v3, v4
	v_mul_hi_u32 v1, v4, v1
	v_add_u32_e32 v1, v4, v1
	v_mul_hi_u32 v1, v5, v1
	v_mul_lo_u32 v3, v1, v2
	v_sub_u32_e32 v3, v5, v3
	v_add_u32_e32 v4, 1, v1
	v_cmp_ge_u32_e32 vcc, v3, v2
	s_nop 1
	v_cndmask_b32_e32 v1, v1, v4, vcc
	v_sub_u32_e32 v4, v3, v2
	v_cndmask_b32_e32 v3, v3, v4, vcc
	v_add_u32_e32 v4, 1, v1
	v_cmp_ge_u32_e32 vcc, v3, v2
	v_add_u32_e32 v3, 1, v5
	s_nop 0
	v_cndmask_b32_e32 v1, v1, v4, vcc
	v_mul_lo_u32 v4, v2, v1
	v_add_u32_e32 v2, v4, v2
	v_cmp_ne_u32_e32 vcc, v3, v2
	s_and_saveexec_b64 s[4:5], vcc
	s_xor_b64 s[10:11], exec, s[4:5]
	s_cbranch_execz .LBB0_75
	s_waitcnt lgkmcnt(0)
	v_mov_b32_e32 v0, 0xa3500
	global_load_dword v0, v0, s[24:25] sc1
	s_add_u32 s16, s24, 0xa3500
	s_addc_u32 s17, s25, 0
	s_waitcnt vmcnt(0)
	v_cmp_eq_u32_e32 vcc, v0, v1
	s_and_saveexec_b64 s[12:13], vcc
	s_cbranch_execz .LBB0_74
	s_add_u32 s14, s24, 0xa0200
	s_addc_u32 s15, s25, 0
	s_mov_b32 s4, 1
	s_mov_b64 s[18:19], 0
	v_mov_b32_e32 v0, 0
	s_branch .LBB0_65

; __device__ __forceinline__ unsigned xb_ld(unsigned* p)              { return __hip_atomic_load(p, __ATOMIC_RELAXED, __HIP_MEMORY_SCOPE_AGENT); }
; __device__ __forceinline__ unsigned xb_add(unsigned* p, unsigned v) { return __hip_atomic_fetch_add(p, v, __ATOMIC_RELAXED, __HIP_MEMORY_SCOPE_AGENT); }
; #define XB_SPIN(cond, bar) do { unsigned _sp = 0; while (cond) { __builtin_amdgcn_s_sleep(1); \
;     if ((++_sp & 255u) == 0u) { if (xb_ld(&(bar)[XB_TMO])) break; if (_sp > XB_SPIN_CAP) { atomicAdd(&(bar)[XB_TMO], 1u); break; } } } } while (0)
; __device__ __forceinline__ void xcd_barrier(const XcdBarrier& b) {
;     ...
;         const unsigned old = xb_add(&bar[XB_XSUB(b.x)], 1u);
;         const unsigned gen = old / nloc;
;         if (old + 1u == (gen + 1u) * nloc) {
;             __builtin_amdgcn_fence(__ATOMIC_RELEASE, "agent");
;             asm volatile("s_waitcnt vmcnt(0)" ::: "memory");
;             const unsigned og = xb_add(&bar[XB_TOP], 1u);
;             const unsigned tg = og / nx;
;             if (og + 1u == (tg + 1u) * nx) xb_add(&bar[XB_TOPGEN], 1u);
;             else XB_SPIN(xb_ld(&bar[XB_TOPGEN]) == tg, bar);
;             __builtin_amdgcn_fence(__ATOMIC_ACQUIRE, "agent");
;             xb_add(&bar[XB_XGEN(b.x)], 1u);
;             asm volatile("s_waitcnt vmcnt(0)" ::: "memory");
;         } else {
;             XB_SPIN(xb_ld(&bar[XB_XGEN(b.x)]) == gen, bar);
;             __builtin_amdgcn_fence(__ATOMIC_ACQUIRE, "agent");
;             asm volatile("s_waitcnt vmcnt(0)" ::: "memory");
;         }
.LBB0_219:
	s_or_b64 exec, exec, s[14:15]
	v_cvt_f32_u32_e32 v4, v2
	s_waitcnt vmcnt(0)
	v_readfirstlane_b32 s0, v3
	buffer_inv sc1
	v_sub_u32_e32 v3, 0, v2
	v_rcp_iflag_f32_e32 v4, v4
	v_add_u32_e32 v5, s0, v1
	v_mul_f32_e32 v4, 0x4f7ffffe, v4
	v_cvt_u32_f32_e32 v4, v4
	v_mul_lo_u32 v1, v3, v4
	v_mul_hi_u32 v1, v4, v1
	v_add_u32_e32 v1, v4, v1
	v_mul_hi_u32 v1, v5, v1
	v_mul_lo_u32 v3, v1, v2
	v_sub_u32_e32 v3, v5, v3
	v_add_u32_e32 v4, 1, v1
	v_cmp_ge_u32_e32 vcc, v3, v2
	s_nop 1
	v_cndmask_b32_e32 v1, v1, v4, vcc
	v_sub_u32_e32 v4, v3, v2
	v_cndmask_b32_e32 v3, v3, v4, vcc
	v_add_u32_e32 v4, 1, v1
	v_cmp_ge_u32_e32 vcc, v3, v2
	v_add_u32_e32 v3, 1, v5
	s_nop 0
	v_cndmask_b32_e32 v1, v1, v4, vcc
	v_mul_lo_u32 v4, v2, v1
	v_add_u32_e32 v2, v4, v2
	v_cmp_ne_u32_e32 vcc, v3, v2
	s_and_saveexec_b64 s[4:5], vcc
	s_xor_b64 s[12:13], exec, s[4:5]
	s_cbranch_execz .LBB0_233
	s_waitcnt lgkmcnt(0)
	v_mov_b32_e32 v0, 0xa3500
	global_load_dword v0, v0, s[24:25] sc1
	s_add_u32 s18, s24, 0xa3500
	s_addc_u32 s19, s25, 0
	s_waitcnt vmcnt(0)
	v_cmp_eq_u32_e32 vcc, v0, v1
	s_and_saveexec_b64 s[14:15], vcc
	s_cbranch_execz .LBB0_232
	s_add_u32 s16, s24, 0xa0200
	s_addc_u32 s17, s25, 0
	s_mov_b32 s4, 1
	s_mov_b64 s[20:21], 0
	v_mov_b32_e32 v0, 0
	s_branch .LBB0_223

; __device__ __forceinline__ unsigned xb_ld(unsigned* p)              { return __hip_atomic_load(p, __ATOMIC_RELAXED, __HIP_MEMORY_SCOPE_AGENT); }
; __device__ __forceinline__ unsigned xb_add(unsigned* p, unsigned v) { return __hip_atomic_fetch_add(p, v, __ATOMIC_RELAXED, __HIP_MEMORY_SCOPE_AGENT); }
; #define XB_SPIN(cond, bar) do { unsigned _sp = 0; while (cond) { __builtin_amdgcn_s_sleep(1); \
;     if ((++_sp & 255u) == 0u) { if (xb_ld(&(bar)[XB_TMO])) break; if (_sp > XB_SPIN_CAP) { atomicAdd(&(bar)[XB_TMO], 1u); break; } } } } while (0)
; __device__ __forceinline__ void xcd_barrier(const XcdBarrier& b) {
;     ...
;         const unsigned old = xb_add(&bar[XB_XSUB(b.x)], 1u);
;         const unsigned gen = old / nloc;
;         if (old + 1u == (gen + 1u) * nloc) {
;             __builtin_amdgcn_fence(__ATOMIC_RELEASE, "agent");
;             asm volatile("s_waitcnt vmcnt(0)" ::: "memory");
;             const unsigned og = xb_add(&bar[XB_TOP], 1u);
;             const unsigned tg = og / nx;
;             if (og + 1u == (tg + 1u) * nx) xb_add(&bar[XB_TOPGEN], 1u);
;             else XB_SPIN(xb_ld(&bar[XB_TOPGEN]) == tg, bar);
;             __builtin_amdgcn_fence(__ATOMIC_ACQUIRE, "agent");
;             xb_add(&bar[XB_XGEN(b.x)], 1u);
;             asm volatile("s_waitcnt vmcnt(0)" ::: "memory");
;         } else {
;             XB_SPIN(xb_ld(&bar[XB_XGEN(b.x)]) == gen, bar);
;             __builtin_amdgcn_fence(__ATOMIC_ACQUIRE, "agent");
;             asm volatile("s_waitcnt vmcnt(0)" ::: "memory");
;         }
.LBB0_311:
	s_or_b64 exec, exec, s[14:15]
	v_cvt_f32_u32_e32 v4, v2
	s_waitcnt vmcnt(0)
	v_readfirstlane_b32 s0, v3
	buffer_inv sc1
	v_sub_u32_e32 v3, 0, v2
	v_rcp_iflag_f32_e32 v4, v4
	v_add_u32_e32 v5, s0, v1
	v_mul_f32_e32 v4, 0x4f7ffffe, v4
	v_cvt_u32_f32_e32 v4, v4
	v_mul_lo_u32 v1, v3, v4
	v_mul_hi_u32 v1, v4, v1
	v_add_u32_e32 v1, v4, v1
	v_mul_hi_u32 v1, v5, v1
	v_mul_lo_u32 v3, v1, v2
	v_sub_u32_e32 v3, v5, v3
	v_add_u32_e32 v4, 1, v1
	v_cmp_ge_u32_e32 vcc, v3, v2
	s_nop 1
	v_cndmask_b32_e32 v1, v1, v4, vcc
	v_sub_u32_e32 v4, v3, v2
	v_cndmask_b32_e32 v3, v3, v4, vcc
	v_add_u32_e32 v4, 1, v1
	v_cmp_ge_u32_e32 vcc, v3, v2
	v_add_u32_e32 v3, 1, v5
	s_nop 0
	v_cndmask_b32_e32 v1, v1, v4, vcc
	v_mul_lo_u32 v4, v2, v1
	v_add_u32_e32 v2, v4, v2
	v_cmp_ne_u32_e32 vcc, v3, v2
	s_and_saveexec_b64 s[4:5], vcc
	s_xor_b64 s[12:13], exec, s[4:5]
	s_cbranch_execz .LBB0_325
	s_waitcnt lgkmcnt(0)
	v_mov_b32_e32 v0, 0xa3500
	global_load_dword v0, v0, s[24:25] sc1
	s_add_u32 s18, s24, 0xa3500
	s_addc_u32 s19, s25, 0
	s_waitcnt vmcnt(0)
	v_cmp_eq_u32_e32 vcc, v0, v1
	s_and_saveexec_b64 s[14:15], vcc
	s_cbranch_execz .LBB0_324
	s_add_u32 s16, s24, 0xa0200
	s_addc_u32 s17, s25, 0
	s_mov_b32 s3, 1
	s_mov_b64 s[20:21], 0
	v_mov_b32_e32 v0, 0
	s_branch .LBB0_315

; __device__ __forceinline__ unsigned xb_ld(unsigned* p)              { return __hip_atomic_load(p, __ATOMIC_RELAXED, __HIP_MEMORY_SCOPE_AGENT); }
; __device__ __forceinline__ unsigned xb_add(unsigned* p, unsigned v) { return __hip_atomic_fetch_add(p, v, __ATOMIC_RELAXED, __HIP_MEMORY_SCOPE_AGENT); }
; #define XB_SPIN(cond, bar) do { unsigned _sp = 0; while (cond) { __builtin_amdgcn_s_sleep(1); \
;     if ((++_sp & 255u) == 0u) { if (xb_ld(&(bar)[XB_TMO])) break; if (_sp > XB_SPIN_CAP) { atomicAdd(&(bar)[XB_TMO], 1u); break; } } } } while (0)
; __device__ __forceinline__ void xcd_barrier(const XcdBarrier& b) {
;     ...
;         const unsigned old = xb_add(&bar[XB_XSUB(b.x)], 1u);
;         const unsigned gen = old / nloc;
;         if (old + 1u == (gen + 1u) * nloc) {
;             __builtin_amdgcn_fence(__ATOMIC_RELEASE, "agent");
;             asm volatile("s_waitcnt vmcnt(0)" ::: "memory");
;             const unsigned og = xb_add(&bar[XB_TOP], 1u);
;             const unsigned tg = og / nx;
;             if (og + 1u == (tg + 1u) * nx) xb_add(&bar[XB_TOPGEN], 1u);
;             else XB_SPIN(xb_ld(&bar[XB_TOPGEN]) == tg, bar);
;             __builtin_amdgcn_fence(__ATOMIC_ACQUIRE, "agent");
;             xb_add(&bar[XB_XGEN(b.x)], 1u);
;             asm volatile("s_waitcnt vmcnt(0)" ::: "memory");
;         } else {
;             XB_SPIN(xb_ld(&bar[XB_XGEN(b.x)]) == gen, bar);
;             __builtin_amdgcn_fence(__ATOMIC_ACQUIRE, "agent");
;             asm volatile("s_waitcnt vmcnt(0)" ::: "memory");
;         }
.LBB0_405:
	s_or_b64 exec, exec, s[12:13]
	v_cvt_f32_u32_e32 v4, v2
	s_waitcnt vmcnt(0)
	v_readfirstlane_b32 s0, v3
	buffer_inv sc1
	v_sub_u32_e32 v3, 0, v2
	v_rcp_iflag_f32_e32 v4, v4
	v_add_u32_e32 v5, s0, v1
	v_mul_f32_e32 v4, 0x4f7ffffe, v4
	v_cvt_u32_f32_e32 v4, v4
	v_mul_lo_u32 v1, v3, v4
	v_mul_hi_u32 v1, v4, v1
	v_add_u32_e32 v1, v4, v1
	v_mul_hi_u32 v1, v5, v1
	v_mul_lo_u32 v3, v1, v2
	v_sub_u32_e32 v3, v5, v3
	v_add_u32_e32 v4, 1, v1
	v_cmp_ge_u32_e32 vcc, v3, v2
	s_nop 1
	v_cndmask_b32_e32 v1, v1, v4, vcc
	v_sub_u32_e32 v4, v3, v2
	v_cndmask_b32_e32 v3, v3, v4, vcc
	v_add_u32_e32 v4, 1, v1
	v_cmp_ge_u32_e32 vcc, v3, v2
	v_add_u32_e32 v3, 1, v5
	s_nop 0
	v_cndmask_b32_e32 v1, v1, v4, vcc
	v_mul_lo_u32 v4, v2, v1
	v_add_u32_e32 v2, v4, v2
	v_cmp_ne_u32_e32 vcc, v3, v2
	s_and_saveexec_b64 s[4:5], vcc
	s_xor_b64 s[10:11], exec, s[4:5]
	s_cbranch_execz .LBB0_419
	s_waitcnt lgkmcnt(0)
	v_mov_b32_e32 v0, 0xa3500
	global_load_dword v0, v0, s[24:25] sc1
	s_add_u32 s16, s24, 0xa3500
	s_addc_u32 s17, s25, 0
	s_waitcnt vmcnt(0)
	v_cmp_eq_u32_e32 vcc, v0, v1
	s_and_saveexec_b64 s[12:13], vcc
	s_cbranch_execz .LBB0_418
	s_add_u32 s14, s24, 0xa0200
	s_addc_u32 s15, s25, 0
	s_mov_b32 s3, 1
	s_mov_b64 s[18:19], 0
	v_mov_b32_e32 v0, 0
	s_branch .LBB0_409

; __device__ __forceinline__ unsigned xb_ld(unsigned* p)              { return __hip_atomic_load(p, __ATOMIC_RELAXED, __HIP_MEMORY_SCOPE_AGENT); }
; __device__ __forceinline__ unsigned xb_add(unsigned* p, unsigned v) { return __hip_atomic_fetch_add(p, v, __ATOMIC_RELAXED, __HIP_MEMORY_SCOPE_AGENT); }
; #define XB_SPIN(cond, bar) do { unsigned _sp = 0; while (cond) { __builtin_amdgcn_s_sleep(1); \
;     if ((++_sp & 255u) == 0u) { if (xb_ld(&(bar)[XB_TMO])) break; if (_sp > XB_SPIN_CAP) { atomicAdd(&(bar)[XB_TMO], 1u); break; } } } } while (0)
; __device__ __forceinline__ void xcd_barrier(const XcdBarrier& b) {
;     ...
;         const unsigned old = xb_add(&bar[XB_XSUB(b.x)], 1u);
;         const unsigned gen = old / nloc;
;         if (old + 1u == (gen + 1u) * nloc) {
;             __builtin_amdgcn_fence(__ATOMIC_RELEASE, "agent");
;             asm volatile("s_waitcnt vmcnt(0)" ::: "memory");
;             const unsigned og = xb_add(&bar[XB_TOP], 1u);
;             const unsigned tg = og / nx;
;             if (og + 1u == (tg + 1u) * nx) xb_add(&bar[XB_TOPGEN], 1u);
;             else XB_SPIN(xb_ld(&bar[XB_TOPGEN]) == tg, bar);
;             __builtin_amdgcn_fence(__ATOMIC_ACQUIRE, "agent");
;             xb_add(&bar[XB_XGEN(b.x)], 1u);
;             asm volatile("s_waitcnt vmcnt(0)" ::: "memory");
;         } else {
;             XB_SPIN(xb_ld(&bar[XB_XGEN(b.x)]) == gen, bar);
;             __builtin_amdgcn_fence(__ATOMIC_ACQUIRE, "agent");
;             asm volatile("s_waitcnt vmcnt(0)" ::: "memory");
;         }
.LBB0_619:
	s_or_b64 exec, exec, s[12:13]
	v_cvt_f32_u32_e32 v4, v2
	s_waitcnt vmcnt(0)
	v_readfirstlane_b32 s0, v3
	buffer_inv sc1
	v_sub_u32_e32 v3, 0, v2
	v_rcp_iflag_f32_e32 v4, v4
	v_add_u32_e32 v5, s0, v1
	v_mul_f32_e32 v4, 0x4f7ffffe, v4
	v_cvt_u32_f32_e32 v4, v4
	v_mul_lo_u32 v1, v3, v4
	v_mul_hi_u32 v1, v4, v1
	v_add_u32_e32 v1, v4, v1
	v_mul_hi_u32 v1, v5, v1
	v_mul_lo_u32 v3, v1, v2
	v_sub_u32_e32 v3, v5, v3
	v_add_u32_e32 v4, 1, v1
	v_cmp_ge_u32_e32 vcc, v3, v2
	s_nop 1
	v_cndmask_b32_e32 v1, v1, v4, vcc
	v_sub_u32_e32 v4, v3, v2
	v_cndmask_b32_e32 v3, v3, v4, vcc
	v_add_u32_e32 v4, 1, v1
	v_cmp_ge_u32_e32 vcc, v3, v2
	v_add_u32_e32 v3, 1, v5
	s_nop 0
	v_cndmask_b32_e32 v1, v1, v4, vcc
	v_mul_lo_u32 v4, v2, v1
	v_add_u32_e32 v2, v4, v2
	v_cmp_ne_u32_e32 vcc, v3, v2
	s_and_saveexec_b64 s[0:1], vcc
	s_xor_b64 s[10:11], exec, s[0:1]
	s_cbranch_execz .LBB0_633
	s_waitcnt lgkmcnt(0)
	v_mov_b32_e32 v0, 0xa3500
	global_load_dword v0, v0, s[24:25] sc1
	s_add_u32 s16, s24, 0xa3500
	s_addc_u32 s17, s25, 0
	s_waitcnt vmcnt(0)
	v_cmp_eq_u32_e32 vcc, v0, v1
	s_and_saveexec_b64 s[12:13], vcc
	s_cbranch_execz .LBB0_632
	s_add_u32 s14, s24, 0xa0200
	s_addc_u32 s15, s25, 0
	s_mov_b32 s3, 1
	s_mov_b64 s[18:19], 0
	v_mov_b32_e32 v0, 0
	s_branch .LBB0_623
